# same as previous best but ret_unit chunk wait ladder back to the original counts
# speedup vs baseline: 1.0145x; 1.0001x over previous
; #define LAS __attribute__((address_space(3)))
; __device__ __forceinline__ int opaque_tid() { int t = threadIdx.x; asm volatile("" : "+v"(t)); return t; }
; __device__ __forceinline__ u32x2 pack4(f32x4 v) { u32x2 r; r.x = cvt_pk_bf16(v[0], v[1]); r.y = cvt_pk_bf16(v[2], v[3]); return r; }
; template <int MODE> __device__ __forceinline__ void ret_unit(LAS unsigned char* lds, const Params& P, int unit, int half) {
;     constexpr int QS = 544, VS = 160;
;     LAS unsigned char* TQ = lds; LAS unsigned char* TK = lds + 34816; LAS unsigned char* TV = lds + 69632; LAS unsigned char* TVD = lds + 79872; LAS unsigned char* AT = lds + 90112; LAS unsigned char* RT = lds + 100352;
;     const int tid = opaque_tid(), lane = tid & 63, w = __builtin_amdgcn_readfirstlane(tid >> 6), quad = lane >> 4, l15 = lane & 15;
;     const int h = unit >> 7, sc = (unit >> 3) & 15, dvs = unit & 7;
;     const bf16_t* Z = (const bf16_t*)(P.ws + WS_Z1);
;     bf16_t* OB = (bf16_t*)(P.ws + WS_OB);
;     float* rssq = (float*)(P.ws + WS_RSSQ) + (size_t)half * HALF_TOK * 8;
;     float* st = (float*)(P.ws + WS_RST) + (size_t)unit * 16384;
;     const float lg2 = ret_log2_gamma(h);
;     const float g64 = exp2f(64.f * lg2);
;     f32x4 R[2][4];
; #pragma unroll
;     for (int i = 0; i < 2; ++i)
; #pragma unroll
;         for (int nt = 0; nt < 4; ++nt) {
;             if (MODE == 0) R[i][nt] = (f32x4){0.f, 0.f, 0.f, 0.f};
;             else {
; #pragma unroll
;                 for (int r = 0; r < 4; ++r) R[i][nt][r] = st[(16 * (2 * w + i) + 4 * quad + r) * 64 + 16 * nt + l15];
;                 *(LAS u32x2*)(RT + (16 * nt + l15) * QS + (16 * (2 * w + i) + 4 * quad) * 2) = pack4(R[i][nt]);
;             }
;         }
.LBB0_50:
	v_mov_b32_e32 v74, v202
	s_lshl_b32 s0, s17, 1
	s_ashr_i32 s7, s6, 31
	v_readfirstlane_b32 s14, v74
	s_and_b32 s33, s28, 0x3c00
	s_and_b32 s31, s0, 0x380
	s_ashr_i32 s25, s14, 6
	s_ashr_i32 s24, s6, 7
	s_lshl_b64 s[0:1], s[6:7], 16
	v_bfe_u32 v32, v74, 4, 2
	s_add_u32 s0, s94, s0
	s_addc_u32 s1, s75, s1
	s_lshl_b32 s15, s25, 5
	s_waitcnt vmcnt(17)
	v_lshlrev_b32_e32 v94, 2, v32
	v_or_b32_e32 v0, s15, v94
	v_and_b32_e32 v73, 15, v74
	v_lshlrev_b32_e32 v22, 6, v0
	v_or_b32_e32 v6, v22, v73
	v_ashrrev_i32_e32 v7, 31, v6
	v_lshl_add_u64 v[0:1], v[6:7], 2, s[0:1]
	v_ashrrev_i32_e32 v7, 31, v22
	v_or_b32_e32 v30, 16, v73
	v_lshl_add_u64 v[10:11], v[6:7], 2, s[0:1]
	v_or_b32_e32 v6, v22, v30
	v_or_b32_e32 v33, 32, v73
	s_waitcnt lgkmcnt(0)
	v_lshl_add_u64 v[14:15], v[6:7], 2, s[0:1]
	v_or_b32_e32 v6, v22, v33
	v_or_b32_e32 v34, 48, v73
	v_lshl_add_u64 v[16:17], v[6:7], 2, s[0:1]
	v_or_b32_e32 v6, v22, v34
	v_or_b32_e32 v35, 0x400, v22
	global_load_dword v0, v[0:1], off
	s_nop 0
	global_load_dword v1, v[10:11], off offset:256
	global_load_dword v2, v[10:11], off offset:512
	global_load_dword v3, v[10:11], off offset:768
	global_load_dword v4, v[10:11], off offset:64
	global_load_dword v5, v[14:15], off offset:256
	global_load_dword v8, v[10:11], off offset:128
	global_load_dword v12, v[10:11], off offset:192
	v_lshl_add_u64 v[18:19], v[6:7], 2, s[0:1]
	global_load_dword v6, v[14:15], off offset:512
	global_load_dword v7, v[14:15], off offset:768
	global_load_dword v9, v[16:17], off offset:256
	global_load_dword v10, v[16:17], off offset:512
	global_load_dword v11, v[16:17], off offset:768
	global_load_dword v13, v[18:19], off offset:256
	s_nop 0
	global_load_dword v14, v[18:19], off offset:512
	global_load_dword v15, v[18:19], off offset:768
	v_or_b32_e32 v16, v35, v73
	v_or_b32_e32 v36, 0x440, v22
	v_or_b32_e32 v37, 0x480, v22
	v_or_b32_e32 v38, 0x4c0, v22
	v_ashrrev_i32_e32 v17, 31, v16
	v_or_b32_e32 v18, v36, v73
	v_or_b32_e32 v20, v37, v73
	v_or_b32_e32 v22, v38, v73
	v_or_b32_e32 v24, v35, v30
	v_or_b32_e32 v26, v36, v30
	v_or_b32_e32 v28, v37, v30
	v_or_b32_e32 v30, v38, v30
	v_lshl_add_u64 v[16:17], v[16:17], 2, s[0:1]
	v_ashrrev_i32_e32 v19, 31, v18
	v_ashrrev_i32_e32 v21, 31, v20
	v_ashrrev_i32_e32 v23, 31, v22
	v_ashrrev_i32_e32 v25, 31, v24
	v_ashrrev_i32_e32 v27, 31, v26
	v_ashrrev_i32_e32 v29, 31, v28
	v_ashrrev_i32_e32 v31, 31, v30
	v_lshl_add_u64 v[18:19], v[18:19], 2, s[0:1]
	v_lshl_add_u64 v[20:21], v[20:21], 2, s[0:1]
	v_lshl_add_u64 v[22:23], v[22:23], 2, s[0:1]
	v_lshl_add_u64 v[24:25], v[24:25], 2, s[0:1]
	v_lshl_add_u64 v[26:27], v[26:27], 2, s[0:1]
	v_lshl_add_u64 v[28:29], v[28:29], 2, s[0:1]
	v_lshl_add_u64 v[30:31], v[30:31], 2, s[0:1]
	global_load_dword v40, v[16:17], off
	global_load_dword v41, v[18:19], off
	global_load_dword v42, v[20:21], off
	global_load_dword v43, v[22:23], off
	global_load_dword v44, v[24:25], off
	global_load_dword v45, v[26:27], off
	global_load_dword v46, v[28:29], off
	global_load_dword v47, v[30:31], off
	v_or_b32_e32 v16, v35, v33
	v_ashrrev_i32_e32 v17, 31, v16
	v_or_b32_e32 v18, v36, v33
	v_or_b32_e32 v20, v37, v33
	v_or_b32_e32 v22, v38, v33
	v_or_b32_e32 v24, v35, v34
	v_or_b32_e32 v26, v36, v34
	v_or_b32_e32 v28, v37, v34
	v_or_b32_e32 v30, v38, v34
	v_lshl_add_u64 v[16:17], v[16:17], 2, s[0:1]
	v_ashrrev_i32_e32 v19, 31, v18
	v_ashrrev_i32_e32 v21, 31, v20
	v_ashrrev_i32_e32 v23, 31, v22
	v_ashrrev_i32_e32 v25, 31, v24
	v_ashrrev_i32_e32 v27, 31, v26
	v_ashrrev_i32_e32 v29, 31, v28
	v_ashrrev_i32_e32 v31, 31, v30
	v_lshl_add_u64 v[18:19], v[18:19], 2, s[0:1]
	v_lshl_add_u64 v[20:21], v[20:21], 2, s[0:1]
	v_lshl_add_u64 v[22:23], v[22:23], 2, s[0:1]
	v_lshl_add_u64 v[24:25], v[24:25], 2, s[0:1]
	v_lshl_add_u64 v[26:27], v[26:27], 2, s[0:1]
	v_lshl_add_u64 v[28:29], v[28:29], 2, s[0:1]
	v_lshl_add_u64 v[30:31], v[30:31], 2, s[0:1]
	global_load_dword v60, v[16:17], off
	global_load_dword v61, v[18:19], off
	global_load_dword v62, v[20:21], off
	global_load_dword v63, v[22:23], off
	global_load_dword v64, v[24:25], off
	global_load_dword v65, v[26:27], off
	global_load_dword v66, v[28:29], off
	global_load_dword v67, v[30:31], off
	s_sub_i32 s0, -5, s24
	v_ldexp_f32 v16, 1.0, s0
	v_fmamk_f32 v17, v16, 0x3e124925, v204
	v_fmaak_f32 v17, v16, v17, 0x3e4ccccd
	v_fmaak_f32 v17, v16, v17, 0x3e800000
	v_fmaak_f32 v17, v16, v17, 0x3eaaaaab
	v_fma_f32 v17, v16, v17, 0.5
	s_and_b32 s34, s14, 0xffffffc0
	v_readlane_b32 s35, v253, 55
	v_fma_f32 v17, v16, v17, 1.0
	v_lshlrev_b32_e32 v90, 3, v32
	s_add_i32 s0, s35, s34
	v_mul_f32_e32 v16, v17, v16
	v_add_u32_e32 v96, s0, v90
	s_movk_i32 s37, 0x220
	v_mul_f32_e32 v78, 0xbfb8aa3b, v16
	v_mad_u32_u24 v26, v73, s37, v96
	s_lshl_b32 s0, s6, 7
	s_waitcnt vmcnt(30)
	v_cvt_pk_bf16_f32 v16, v0, v1
	s_and_b32 s29, s0, 0x3c00
	s_waitcnt vmcnt(28)
	v_cvt_pk_bf16_f32 v17, v2, v3
	s_waitcnt vmcnt(22)
	v_cvt_pk_bf16_f32 v19, v6, v7
	v_cvt_pk_bf16_f32 v18, v4, v5
	s_waitcnt vmcnt(21)
	v_cvt_pk_bf16_f32 v20, v8, v9
	s_waitcnt vmcnt(19)
	v_cvt_pk_bf16_f32 v21, v10, v11
	s_waitcnt vmcnt(18)
	v_cvt_pk_bf16_f32 v22, v12, v13
	s_waitcnt vmcnt(16)
	v_cvt_pk_bf16_f32 v23, v14, v15
	s_lshl_b32 s0, s24, 8
	v_ashrrev_i32_e32 v86, 5, v74
	s_ashr_i32 s1, s0, 31
	v_mov_b64_e32 v[56:57], s[72:73]
	s_lshl_b64 s[26:27], s[0:1], 1
	v_lshlrev_b32_e32 v58, 4, v74
	v_and_b32_e32 v180, 0x1f0, v58
	v_add_u32_e32 v32, 0x400, v74
	v_ashrrev_i32_e32 v82, 5, v32
	v_add_u32_e32 v32, s29, v82
	v_add_u32_e32 v48, 0x600, v74
	v_mad_i64_i32 v[32:33], s[0:1], v32, s22, v[56:57]
	v_ashrrev_i32_e32 v80, 5, v48
	v_lshl_add_u64 v[32:33], v[32:33], 0, s[26:27]
	v_add_u32_e32 v48, s29, v80
	v_lshl_add_u64 v[36:37], v[32:33], 0, v[180:181]
	v_mad_i64_i32 v[48:49], s[0:1], v48, s22, v[56:57]
	v_lshl_add_u64 v[48:49], v[48:49], 0, s[26:27]
	v_lshl_add_u64 v[52:53], v[48:49], 0, v[180:181]
	s_waitcnt vmcnt(14)
; #define LAS __attribute__((address_space(3)))
; __device__ __forceinline__ u32x2 pack4(f32x4 v) { u32x2 r; r.x = cvt_pk_bf16(v[0], v[1]); r.y = cvt_pk_bf16(v[2], v[3]); return r; }
; template <int MODE> __device__ __forceinline__ void ret_unit(LAS unsigned char* lds, const Params& P, int unit, int half) {
;     ...
;                 for (int r = 0; r < 4; ++r) R[i][nt][r] = st[(16 * (2 * w + i) + 4 * quad + r) * 64 + 16 * nt + l15];
;                 *(LAS u32x2*)(RT + (16 * nt + l15) * QS + (16 * (2 * w + i) + 4 * quad) * 2) = pack4(R[i][nt]);
;             }
;         }
;     u32x4 rq[4], rk[4], rv;
;     ...
;     RET_LOAD(0);
;     ...
;           const float d = exp2f((float)(63 - r) * lg2);
	v_cvt_pk_bf16_f32 v24, v40, v41
	v_mul_f32_e32 v50, 0x42800000, v78
	s_waitcnt vmcnt(12)
	v_cvt_pk_bf16_f32 v25, v42, v43
	ds_write2_b64 v26, v[16:17], v[24:25] offset1:4
	s_waitcnt vmcnt(10)
	v_cvt_pk_bf16_f32 v16, v44, v45
	v_add_u32_e32 v24, 0x2000, v26
	s_waitcnt vmcnt(8)
	v_cvt_pk_bf16_f32 v17, v46, v47
	ds_write2_b64 v24, v[18:19], v[16:17] offset0:64 offset1:68
	v_add_u32_e32 v18, 0x4000, v26
	v_add_u32_e32 v24, 0x200, v74
	v_ashrrev_i32_e32 v84, 5, v24
	v_add_u32_e32 v24, s29, v84
	v_mad_i64_i32 v[24:25], s[0:1], v24, s22, v[56:57]
	v_lshl_add_u64 v[24:25], v[24:25], 0, s[26:27]
	v_lshl_add_u64 v[28:29], v[24:25], 0, v[180:181]
	s_mov_b32 s52, 0xc2fc0000
	v_ashrrev_i32_e32 v79, 3, v74
	v_and_b32_e32 v92, 0x70, v58
	v_mov_b32_e32 v93, v181
	s_movk_i32 s54, 0xa0
	v_and_b32_e32 v75, 63, v74
	v_and_b32_e32 v132, 48, v74
	v_bfe_u32 v87, v74, 2, 2
	v_xor_b32_e32 v89, 32, v208
	s_waitcnt vmcnt(6)
	v_cvt_pk_bf16_f32 v16, v60, v61
	v_readlane_b32 s56, v253, 58
	s_waitcnt vmcnt(4)
	v_cvt_pk_bf16_f32 v17, v62, v63
	ds_write2_b64 v18, v[20:21], v[16:17] offset0:128 offset1:132
	s_waitcnt vmcnt(2)
	v_cvt_pk_bf16_f32 v16, v64, v65
	v_add_u32_e32 v18, 0x6000, v26
	s_waitcnt vmcnt(0)
	v_cvt_pk_bf16_f32 v17, v66, v67
	ds_write2_b64 v18, v[22:23], v[16:17] offset0:192 offset1:196
	v_add_u32_e32 v16, s29, v86
	v_mad_i64_i32 v[16:17], s[20:21], v16, s22, v[56:57]
	v_lshl_add_u64 v[16:17], v[16:17], 0, s[26:27]
	v_lshl_add_u64 v[20:21], v[16:17], 0, v[180:181]
	v_add_co_u32_e32 v16, vcc, s78, v20
	v_mul_lo_u32 v76, v79, s54
	s_nop 0
	v_addc_co_u32_e32 v17, vcc, 0, v21, vcc
	v_add_co_u32_e32 v24, vcc, s78, v28
	global_load_dwordx4 v[16:19], v[16:17], off
	s_nop 0
	global_load_dwordx4 v[20:23], v[20:21], off
	v_addc_co_u32_e32 v25, vcc, 0, v29, vcc
	v_add_co_u32_e32 v32, vcc, s78, v36
	global_load_dwordx4 v[24:27], v[24:25], off
	s_nop 0
	global_load_dwordx4 v[28:31], v[28:29], off
	v_addc_co_u32_e32 v33, vcc, 0, v37, vcc
	v_add_co_u32_e32 v48, vcc, s78, v52
	global_load_dwordx4 v[32:35], v[32:33], off
	s_nop 0
	global_load_dwordx4 v[36:39], v[36:37], off
	v_addc_co_u32_e32 v49, vcc, 0, v53, vcc
	v_cmp_gt_f32_e32 vcc, s52, v50
	s_and_b64 s[0:1], vcc, exec
	s_cselect_b32 s0, 0xffffffc0, 0
	v_cndmask_b32_e32 v50, 0, v206, vcc
	v_fmac_f32_e32 v50, 0x42800000, v78
	v_exp_f32_e32 v59, v50
	global_load_dwordx4 v[48:51], v[48:49], off
	s_nop 0
	global_load_dwordx4 v[52:55], v[52:53], off
	v_readlane_b32 s55, v253, 56
	v_mul_lo_u32 v118, v86, s37
	v_ldexp_f32 v72, v59, s0
	v_add_u32_e32 v59, s29, v79
	v_mad_i64_i32 v[56:57], s[0:1], v59, s22, v[56:57]
	s_lshl_b32 s0, s24, 9
	s_ashr_i32 s1, s0, 31
	s_lshl_b64 s[20:21], s[0:1], 1
	s_lshl_b32 s0, s6, 6
	s_and_b32 s30, s0, 0x1c0
	v_lshl_add_u64 v[56:57], v[56:57], 0, s[20:21]
	s_lshl_b32 s22, s30, 1
	v_lshl_add_u64 v[56:57], v[56:57], 0, s[22:23]
	v_lshl_add_u64 v[56:57], v[56:57], 0, v[92:93]
	s_movk_i32 s0, 0x2000
	v_add_co_u32_e32 v56, vcc, s0, v56
	s_lshl_b32 s0, s25, 4
	s_and_b32 s22, s0, 48
	s_ashr_i32 s0, s14, 3
	s_and_b32 s14, s0, 0xffffffe0
	v_or_b32_e32 v81, s14, v73
	v_readlane_b32 s0, v253, 57
	v_or_b32_e32 v98, s22, v73
	v_mul_lo_u32 v69, v81, s54
	v_mov_b32_e32 v77, s0
	v_add_u32_e32 v99, s0, v69
	v_add_u32_e32 v69, 1, v98
	v_mad_u32_u24 v135, v98, s54, v77
	v_lshrrev_b32_e32 v77, 1, v74
	v_lshlrev_b32_e32 v74, 2, v74
	v_cvt_f32_ubyte0_e32 v69, v69
	v_and_b32_e32 v88, 12, v74
	v_addc_co_u32_e32 v57, vcc, 0, v57, vcc
	v_mul_f32_e32 v70, v78, v69
	v_and_or_b32 v87, v77, 24, v87
	v_or_b32_e32 v74, s14, v88
	v_and_b32_e32 v77, 64, v208
	v_cmp_gt_f32_e32 vcc, s52, v70
	v_lshlrev_b32_e32 v136, 1, v74
	v_xor_b32_e32 v74, 16, v208
	v_add_u32_e32 v77, 64, v77
	v_cndmask_b32_e32 v70, 0, v207, vcc
	v_cndmask_b32_e32 v71, 0, v206, vcc
	v_cmp_lt_i32_e32 vcc, v74, v77
	global_load_dwordx4 v[56:59], v[56:57], off
	v_or_b32_e32 v83, s22, v94
	v_cndmask_b32_e32 v74, v208, v74, vcc
	v_lshlrev_b32_e32 v93, 2, v74
	v_sub_u32_e32 v74, 63, v79
	v_cvt_f32_i32_e32 v74, v74
	v_cmp_lt_i32_e32 vcc, v89, v77
	v_lshlrev_b32_e32 v107, 1, v88
	v_or_b32_e32 v85, 16, v81
	v_cndmask_b32_e32 v77, v208, v89, vcc
	v_mul_f32_e32 v89, v78, v74
	v_cmp_gt_f32_e64 s[0:1], s52, v89
	v_cmp_gt_u32_e32 vcc, 16, v75
	v_lshlrev_b32_e32 v101, 1, v83
	v_cndmask_b32_e64 v89, 0, v206, s[0:1]
	v_fmac_f32_e32 v89, v78, v74
	v_exp_f32_e32 v74, v89
	v_cndmask_b32_e64 v75, 0, v207, s[0:1]
	v_sub_u32_e32 v89, v85, v83
	v_cmp_lt_i32_e64 s[40:41], -1, v89
	v_ldexp_f32 v74, v74, v75
	v_or_b32_e32 v75, s15, v88
	v_lshlrev_b32_e32 v106, 1, v75
	v_sub_u32_e32 v75, v81, v83
	v_cvt_f32_u32_e32 v88, v75
	v_cmp_lt_i32_e64 s[38:39], -1, v75
	v_cvt_f32_u32_e32 v75, v89
	v_mul_lo_u32 v68, v81, s37
	v_mul_f32_e32 v91, v78, v88
	v_cmp_gt_f32_e64 s[0:1], s52, v91
	v_fmac_f32_e32 v71, v78, v69
	v_add_u32_e32 v134, s35, v68
	v_cndmask_b32_e64 v91, 0, v206, s[0:1]
	v_fmac_f32_e32 v91, v78, v88
	v_exp_f32_e32 v88, v91
	v_cndmask_b32_e64 v91, 0, v207, s[0:1]
	s_movk_i32 s35, 0x6000
	v_mul_lo_u32 v119, v84, s37
	v_ldexp_f32 v100, v88, v91
	v_mul_f32_e32 v88, v78, v75
	v_cmp_gt_f32_e64 s[0:1], s52, v88
	v_mul_lo_u32 v120, v82, s37
	v_mul_lo_u32 v137, v80, s37
; template <int MODE> __device__ __forceinline__ void ret_unit(LAS unsigned char* lds, const Params& P, int unit, int half) {
;     ...
;           const float d = exp2f((float)(63 - r) * lg2);
;     ...
;                 const int sb = 16 * ms + 4 * quad, ta = 16 * nt0 + l15, tb = ta + 16;
; #pragma unroll
;                 for (int r = 0; r < 4; ++r) {
;                     const int da = ta - (sb + r), db = tb - (sb + r);
;                     c0[r] = da >= 0 ? c0[r] * exp2f((float)da * lg2) : 0.f;
;                     c1[r] = db >= 0 ? c1[r] * exp2f((float)db * lg2) : 0.f;
;                 }
;     ...
;                 const float qd = exp2f((float)(16 * nt + l15 + 1) * lg2);
	v_cndmask_b32_e64 v88, 0, v206, s[0:1]
	v_fmac_f32_e32 v88, v78, v75
	v_exp_f32_e32 v75, v88
	v_or_b32_e32 v88, 1, v83
	v_sub_u32_e32 v89, v81, v88
	v_cvt_f32_u32_e32 v91, v89
	v_cndmask_b32_e64 v102, 0, v207, s[0:1]
	v_ldexp_f32 v102, v75, v102
	v_sub_u32_e32 v75, v85, v88
	v_cmp_lt_i32_e64 s[42:43], -1, v89
	v_cvt_f32_u32_e32 v89, v75
	v_mul_f32_e32 v88, v78, v91
	v_cmp_gt_f32_e64 s[0:1], s52, v88
	v_cmp_lt_i32_e64 s[44:45], -1, v75
	v_mul_f32_e32 v75, v78, v89
	v_cndmask_b32_e64 v88, 0, v206, s[0:1]
	v_fmac_f32_e32 v88, v78, v91
	v_exp_f32_e32 v88, v88
	v_cndmask_b32_e64 v91, 0, v207, s[0:1]
	v_cmp_gt_f32_e64 s[0:1], s52, v75
	v_add_u32_e32 v80, s33, v80
	v_ldexp_f32 v103, v88, v91
	v_cndmask_b32_e64 v75, 0, v206, s[0:1]
	v_fmac_f32_e32 v75, v78, v89
	v_exp_f32_e32 v75, v75
	v_or_b32_e32 v88, 2, v83
	v_sub_u32_e32 v89, v81, v88
	v_cvt_f32_u32_e32 v91, v89
	v_cndmask_b32_e64 v104, 0, v207, s[0:1]
	v_ldexp_f32 v104, v75, v104
	v_sub_u32_e32 v75, v85, v88
	v_cmp_lt_i32_e64 s[46:47], -1, v89
	v_cvt_f32_u32_e32 v89, v75
	v_mul_f32_e32 v88, v78, v91
	v_cmp_gt_f32_e64 s[0:1], s52, v88
	v_cmp_lt_i32_e64 s[48:49], -1, v75
	v_mul_f32_e32 v75, v78, v89
	v_cndmask_b32_e64 v88, 0, v206, s[0:1]
	v_fmac_f32_e32 v88, v78, v91
	v_cndmask_b32_e64 v91, 0, v207, s[0:1]
	v_cmp_gt_f32_e64 s[0:1], s52, v75
	v_exp_f32_e32 v88, v88
	v_or_b32_e32 v83, 3, v83
	v_cndmask_b32_e64 v75, 0, v206, s[0:1]
	v_fmac_f32_e32 v75, v78, v89
	v_exp_f32_e32 v75, v75
	v_ldexp_f32 v105, v88, v91
	v_cndmask_b32_e64 v88, 0, v207, s[0:1]
	v_sub_u32_e32 v81, v81, v83
	v_cvt_f32_u32_e32 v89, v81
	v_ldexp_f32 v108, v75, v88
	v_sub_u32_e32 v75, v85, v83
	v_cvt_f32_u32_e32 v83, v75
	v_cmp_lt_i32_e64 s[50:51], -1, v81
	v_mul_f32_e32 v81, v78, v89
	v_cmp_gt_f32_e64 s[0:1], s52, v81
	v_mul_f32_e32 v88, v78, v83
	v_add_u32_e32 v82, s33, v82
	v_cndmask_b32_e64 v81, 0, v206, s[0:1]
	v_cndmask_b32_e64 v85, 0, v207, s[0:1]
	v_cmp_gt_f32_e64 s[0:1], s52, v88
	v_fmac_f32_e32 v81, v78, v89
	v_cmp_lt_i32_e64 s[52:53], -1, v75
	v_cndmask_b32_e64 v88, 0, v206, s[0:1]
	v_fmac_f32_e32 v88, v78, v83
	v_exp_f32_e32 v78, v88
	v_cndmask_b32_e64 v75, 0, v207, s[0:1]
	s_add_i32 s0, s34, 0
	v_exp_f32_e32 v81, v81
	v_ldexp_f32 v112, v78, v75
	v_mov_b32_e32 v78, s56
	v_mad_u32_u24 v122, v87, s54, v78
	s_add_i32 s0, s0, 0x18820
	v_add_u32_e32 v78, s33, v79
	v_add_u32_e32 v131, s0, v90
	v_mad_i64_i32 v[78:79], s[0:1], v78, s35, 0
	v_mov_b32_e32 v75, s55
	v_or3_b32 v78, v78, s31, v92
	v_mad_u32_u24 v138, v87, s54, v75
	v_mov_b32_e32 v75, 0x1400
	v_lshl_add_u64 v[78:79], v[78:79], 0, s[20:21]
	s_mov_b64 s[0:1], 0x19d82000
	v_add_u32_e32 v84, s33, v84
	v_add_u32_e32 v86, s33, v86
	s_ashr_i32 s25, s24, 31
	v_ldexp_f32 v111, v81, v85
	v_mad_u32_u24 v75, v87, s54, v75
	v_mad_u32_u24 v116, v87, s37, 0
	v_lshl_add_u64 v[78:79], v[78:79], 0, s[0:1]
	v_mad_i64_i32 v[80:81], s[0:1], v80, s35, 0
	v_mad_i64_i32 v[82:83], s[0:1], v82, s35, 0
	v_mad_i64_i32 v[84:85], s[0:1], v84, s35, 0
	v_mad_i64_i32 v[86:87], s[0:1], v86, s35, 0
	s_ashr_i32 s15, s14, 31
	s_or_b32 s0, s33, s22
	s_lshl_b64 s[24:25], s[24:25], 2
	v_mul_u32_u24_e32 v97, 0x220, v73
	v_exp_f32_e32 v69, v71
	v_or_b32_e32 v73, s0, v73
	s_add_u32 s0, s24, s16
	v_add_u32_e32 v109, 0, v180
	v_or_b32_e32 v80, v80, v180
	v_or_b32_e32 v82, v82, v180
	v_or_b32_e32 v84, v84, v180
	v_or_b32_e32 v86, v86, v180
	v_lshlrev_b32_e32 v180, 5, v73
	s_addc_u32 s1, s25, 0
	v_lshl_add_u64 v[88:89], s[0:1], 0, v[180:181]
	s_lshl_b64 s[0:1], s[14:15], 1
	v_add_u32_e32 v117, s56, v75
	v_lshlrev_b32_e32 v73, 13, v73
	s_add_u32 s0, s0, s20
	v_add_u32_e32 v110, s55, v76
	v_mad_u32_u24 v113, v98, s37, 0
	v_add_u32_e32 v115, 0, v68
	v_add_u32_e32 v133, 0xa00, v99
	v_ldexp_f32 v68, v69, v70
	v_add_u32_e32 v114, s56, v76
	v_add_u32_e32 v139, s55, v75
	v_add_u32_e32 v121, 0x880, v116
	v_add_u32_e32 v123, 0xffffee80, v117
	v_add_u32_e32 v128, 0x4400, v116
	v_add_u32_e32 v129, 0x4c80, v116
	v_add_u32_e32 v130, 0x280, v117
	v_or3_b32 v180, v73, s31, v90
	s_addc_u32 s1, s1, s21
	s_mov_b32 s7, 15
	v_mov_b32_e32 v69, v68
	v_mov_b32_e32 v70, v68
	v_mov_b32_e32 v71, v68
	v_lshlrev_b32_e32 v95, 2, v77
	v_mov_b32_e32 v76, v72
	v_mov_b32_e32 v77, v72
	v_mov_b32_e32 v75, v74
	v_lshl_add_u64 v[80:81], v[80:81], 0, s[26:27]
	v_lshl_add_u64 v[82:83], v[82:83], 0, s[26:27]
	v_lshl_add_u64 v[84:85], v[84:85], 0, s[26:27]
	v_lshl_add_u64 v[86:87], v[86:87], 0, s[26:27]
	v_lshl_add_u64 v[90:91], s[0:1], 0, v[180:181]
	v_add_u32_e32 v124, v114, v92
	v_add_u32_e32 v125, v121, v106
	v_add_u32_e32 v126, v122, v107
	v_add_u32_e32 v127, v123, v107
	v_add_u32_e32 v128, v128, v106
	v_add_u32_e32 v129, v129, v106
	v_add_u32_e32 v130, v130, v107
	v_add_u32_e32 v131, v131, v97
	v_add_u32_e32 v123, v109, v118
	v_add_u32_e32 v122, v109, v119
	v_add_u32_e32 v121, v109, v120
	v_add_u32_e32 v119, v109, v137
	v_add_u32_e32 v120, v110, v92
	v_add_u32_e32 v114, v113, v132
	v_add_u32_e32 v118, v115, v132
	v_add_u32_e32 v115, v133, v101
	v_add_u32_e32 v113, v134, v132
	v_add_u32_e32 v109, v135, v132
	v_add_u32_e32 v110, v138, v136
	v_add_u32_e32 v92, v139, v136
	s_mov_b32 s22, 0x19d81000
	s_mov_b32 s31, 0x19d80000
	s_branch .LBB0_52

; #define LAS __attribute__((address_space(3)))
; __device__ __forceinline__ unsigned cvt_pk_bf16(float lo, float hi) { const f32v2_t v = {lo, hi}; const bf16v2_t r = __builtin_convertvector(v, bf16v2_t); return __builtin_bit_cast(unsigned, r); }
; template <int MODE> __device__ __forceinline__ void ret_unit(LAS unsigned char* lds, const Params& P, int unit, int half) {
;     ...
;     for (int c = 0; c < 16; ++c) {
;         const int r0 = sc * 1024 + 64 * c;
; #pragma unroll
;         for (int i = 0; i < 4; ++i) { const int ch = tid + 512 * i, r = ch >> 5, cc = ch & 31;
;             *(LAS u32x4*)(TK + r * QS + cc * 16) = rk[i];
;             if (MODE == 1) *(LAS u32x4*)(TQ + r * QS + cc * 16) = rq[i]; }
;         { const int r = tid >> 3, cc = tid & 7;
;           if (MODE == 1) *(LAS u32x4*)(TV + r * VS + cc * 16) = rv;
;           if (MODE == 0 || c < 15) {
;           const float d = exp2f((float)(63 - r) * lg2);
;           u32x4 vd;
; #pragma unroll
;           for (int j = 0; j < 4; ++j) vd[j] = cvt_pk_bf16(bflo(rv[j]) * d, bfhi(rv[j]) * d);
;           *(LAS u32x4*)(TVD + r * VS + cc * 16) = vd; } }
;         __syncthreads();
;         if (c + 1 < 16) RET_LOAD(c + 1);
;         if (MODE == 1) {
;             {
;                 const int ms = w & 3, nt0 = 2 * (w >> 2);
;                 f32x4 c0 = {0.f, 0.f, 0.f, 0.f}, c1 = {0.f, 0.f, 0.f, 0.f};
;                 bf16x8 fa[8], fb0[8], fb1[8];
; #pragma unroll
;                 for (int ks = 0; ks < 8; ++ks) { fa[ks] = rowfrag(TK, QS, 16 * ms, 32 * ks, lane); fb0[ks] = rowfrag(TQ, QS, 16 * nt0, 32 * ks, lane); fb1[ks] = rowfrag(TQ, QS, 16 * nt0 + 16, 32 * ks, lane); }
;                 __builtin_amdgcn_sched_barrier(0);
; #pragma unroll
;                 for (int ks = 0; ks < 8; ++ks) { c0 = mfma16(fa[ks], fb0[ks], c0); c1 = mfma16(fa[ks], fb1[ks], c1); }
;                 const int sb = 16 * ms + 4 * quad, ta = 16 * nt0 + l15, tb = ta + 16;
; #pragma unroll
;                 for (int r = 0; r < 4; ++r) {
;                     const int da = ta - (sb + r), db = tb - (sb + r);
;                     c0[r] = da >= 0 ? c0[r] * exp2f((float)da * lg2) : 0.f;
;                     c1[r] = db >= 0 ? c1[r] * exp2f((float)db * lg2) : 0.f;
;                 }
;                 *(LAS u32x2*)(AT + ta * VS + sb * 2) = pack4(c0);
;                 *(LAS u32x2*)(AT + tb * VS + sb * 2) = pack4(c1);
;             }
.LBB0_52:
	s_waitcnt vmcnt(8)
	ds_write_b128 v123, v[16:19] offset:34816
	s_waitcnt vmcnt(7)
	ds_write_b128 v123, v[20:23]
	s_waitcnt vmcnt(6)
	ds_write_b128 v122, v[24:27] offset:34816
	s_waitcnt vmcnt(5)
	ds_write_b128 v122, v[28:31]
	s_waitcnt vmcnt(4)
	ds_write_b128 v121, v[32:35] offset:34816
	s_waitcnt vmcnt(3)
	ds_write_b128 v121, v[36:39]
	s_waitcnt vmcnt(2)
	ds_write_b128 v119, v[48:51] offset:34816
	s_waitcnt vmcnt(1)
	ds_write_b128 v119, v[52:55]
	s_waitcnt vmcnt(0)
	ds_write_b128 v120, v[56:59]
	v_lshlrev_b32_e32 v16, 16, v56
	v_and_b32_e32 v17, 0xffff0000, v56
	v_lshlrev_b32_e32 v18, 16, v57
	v_and_b32_e32 v19, 0xffff0000, v57
	v_pk_mul_f32 v[16:17], v[74:75], v[16:17]
	v_pk_mul_f32 v[18:19], v[74:75], v[18:19]
	v_cvt_pk_bf16_f32 v16, v16, v17
	v_cvt_pk_bf16_f32 v17, v18, v19
	v_lshlrev_b32_e32 v18, 16, v58
	v_and_b32_e32 v19, 0xffff0000, v58
	v_lshlrev_b32_e32 v20, 16, v59
	v_and_b32_e32 v21, 0xffff0000, v59
	v_pk_mul_f32 v[18:19], v[74:75], v[18:19]
	v_pk_mul_f32 v[20:21], v[74:75], v[20:21]
	v_cvt_pk_bf16_f32 v18, v18, v19
	v_cvt_pk_bf16_f32 v19, v20, v21
	ds_write_b128 v124, v[16:19]
	v_lshl_add_u64 v[16:17], s[92:93], 0, v[86:87]
	v_add_co_u32_e64 v18, s[0:1], s22, v16
	v_lshl_add_u64 v[24:25], s[92:93], 0, v[84:85]
	s_nop 0
	v_addc_co_u32_e64 v19, s[0:1], 0, v17, s[0:1]
	v_add_co_u32_e64 v20, s[0:1], s31, v16
	v_lshl_add_u64 v[32:33], s[92:93], 0, v[82:83]
	s_nop 0
	v_addc_co_u32_e64 v21, s[0:1], 0, v17, s[0:1]
	v_add_co_u32_e64 v26, s[0:1], s22, v24
	v_lshl_add_u64 v[48:49], s[92:93], 0, v[80:81]
	s_nop 0
	v_addc_co_u32_e64 v27, s[0:1], 0, v25, s[0:1]
	v_add_co_u32_e64 v28, s[0:1], s31, v24
	v_lshl_add_u64 v[56:57], s[92:93], 0, v[78:79]
	s_nop 0
	v_addc_co_u32_e64 v29, s[0:1], 0, v25, s[0:1]
	v_add_co_u32_e64 v34, s[0:1], s22, v32
	s_waitcnt lgkmcnt(0)
	s_nop 0
	v_addc_co_u32_e64 v35, s[0:1], 0, v33, s[0:1]
	v_add_co_u32_e64 v36, s[0:1], s31, v32
	s_barrier
	s_nop 0
	v_addc_co_u32_e64 v37, s[0:1], 0, v33, s[0:1]
	v_add_co_u32_e64 v50, s[0:1], s22, v48
	s_nop 1
	v_addc_co_u32_e64 v51, s[0:1], 0, v49, s[0:1]
	v_add_co_u32_e64 v52, s[0:1], s31, v48
	global_load_dwordx4 v[16:19], v[18:19], off
	s_nop 0
	global_load_dwordx4 v[20:23], v[20:21], off
	v_addc_co_u32_e64 v53, s[0:1], 0, v49, s[0:1]
	global_load_dwordx4 v[24:27], v[26:27], off
	s_nop 0
	global_load_dwordx4 v[28:31], v[28:29], off
	s_nop 0
	global_load_dwordx4 v[32:35], v[34:35], off
	s_nop 0
	global_load_dwordx4 v[36:39], v[36:37], off
	s_nop 0
	global_load_dwordx4 v[48:51], v[50:51], off
	s_nop 0
	global_load_dwordx4 v[52:55], v[52:53], off
	s_nop 0
	global_load_dwordx4 v[56:59], v[56:57], off
	ds_read_b128 v[132:135], v114 offset:34816
	ds_read_b128 v[136:139], v114 offset:34880
	ds_read_b128 v[140:143], v118
	ds_read_b128 v[144:147], v118 offset:64
	ds_read_b128 v[148:151], v118 offset:8704
	ds_read_b128 v[152:155], v118 offset:8768
	ds_read_b128 v[156:159], v114 offset:34944
	ds_read_b128 v[160:163], v114 offset:35008
	ds_read_b128 v[164:167], v118 offset:128
	ds_read_b128 v[168:171], v118 offset:192
	ds_read_b128 v[172:175], v118 offset:8832
	ds_read_b128 v[176:179], v118 offset:8896
	ds_read_b128 v[182:185], v114 offset:35072
	ds_read_b128 v[186:189], v114 offset:35136
	ds_read_b128 v[190:193], v118 offset:256
	ds_read_b128 v[194:197], v118 offset:320
	ds_read_b128 v[198:201], v118 offset:8960
	ds_read_b128 v[214:217], v118 offset:9024
	ds_read_b128 v[218:221], v114 offset:35200
	ds_read_b128 v[222:225], v114 offset:35264
	ds_read_b128 v[226:229], v118 offset:384
	ds_read_b128 v[230:233], v118 offset:448
	ds_read_b128 v[234:237], v118 offset:9088
	ds_read_b128 v[238:241], v118 offset:9152
	s_waitcnt lgkmcnt(14)
	v_mfma_f32_16x16x32_bf16 v[140:143], v[132:135], v[140:143], 0
	v_mfma_f32_16x16x32_bf16 v[132:135], v[132:135], v[148:151], 0
	v_mfma_f32_16x16x32_bf16 v[132:135], v[136:139], v[152:155], v[132:135]
	v_mfma_f32_16x16x32_bf16 v[140:143], v[136:139], v[144:147], v[140:143]
	s_waitcnt lgkmcnt(13)
	v_mfma_f32_16x16x32_bf16 v[132:135], v[156:159], v[172:175], v[132:135]
	v_mfma_f32_16x16x32_bf16 v[136:139], v[156:159], v[164:167], v[140:143]
	s_waitcnt lgkmcnt(12)
	v_mfma_f32_16x16x32_bf16 v[132:135], v[160:163], v[176:179], v[132:135]
	v_mfma_f32_16x16x32_bf16 v[136:139], v[160:163], v[168:171], v[136:139]
	s_waitcnt lgkmcnt(7)
	v_mfma_f32_16x16x32_bf16 v[132:135], v[182:185], v[198:201], v[132:135]
	v_mfma_f32_16x16x32_bf16 v[136:139], v[182:185], v[190:193], v[136:139]
	s_waitcnt lgkmcnt(6)
	v_mfma_f32_16x16x32_bf16 v[132:135], v[186:189], v[214:217], v[132:135]
	v_mfma_f32_16x16x32_bf16 v[136:139], v[186:189], v[194:197], v[136:139]
	s_waitcnt lgkmcnt(1)
	v_mfma_f32_16x16x32_bf16 v[132:135], v[218:221], v[234:237], v[132:135]
	v_mfma_f32_16x16x32_bf16 v[136:139], v[218:221], v[226:229], v[136:139]
	s_waitcnt lgkmcnt(0)
	v_mfma_f32_16x16x32_bf16 v[132:135], v[222:225], v[238:241], v[132:135]
	v_mfma_f32_16x16x32_bf16 v[136:139], v[222:225], v[230:233], v[136:139]
	s_nop 6
	v_mul_f32_e32 v132, v102, v132
	v_mul_f32_e32 v134, v108, v134
	v_mul_f32_e32 v73, v100, v136
	v_cndmask_b32_e64 v136, 0, v132, s[40:41]
	v_mul_f32_e32 v132, v103, v137
	v_mul_f32_e32 v137, v105, v138
	v_cndmask_b32_e64 v138, 0, v134, s[48:49]
	v_mul_f32_e32 v134, v111, v139
	v_cndmask_b32_e64 v73, 0, v73, s[38:39]
	v_cndmask_b32_e64 v132, 0, v132, s[42:43]
	v_mul_f32_e32 v133, v104, v133
	v_cndmask_b32_e64 v137, 0, v137, s[46:47]
	v_cndmask_b32_e64 v139, 0, v134, s[50:51]
	v_mul_f32_e32 v134, v112, v135
	v_cndmask_b32_e64 v133, 0, v133, s[44:45]
	v_cndmask_b32_e64 v140, 0, v134, s[52:53]
	v_cvt_pk_bf16_f32 v134, v73, v132
	v_cvt_pk_bf16_f32 v135, v137, v139
	v_add_u32_e32 v132, v99, v101
	ds_write_b64 v132, v[134:135]
	v_cvt_pk_bf16_f32 v134, v136, v133
	v_cvt_pk_bf16_f32 v135, v138, v140
	ds_write_b64 v115, v[134:135]
	s_waitcnt lgkmcnt(0)
	s_barrier
; __device__ __forceinline__ f32x4 mfma16(bf16x8 a, bf16x8 b, f32x4 c) { return __builtin_amdgcn_mfma_f32_16x16x32_bf16(a, b, c, 0, 0, 0); }
; __device__ __forceinline__ u32x2 pack4(f32x4 v) { u32x2 r; r.x = cvt_pk_bf16(v[0], v[1]); r.y = cvt_pk_bf16(v[2], v[3]); return r; }
; template <int MODE> __device__ __forceinline__ void ret_unit(LAS unsigned char* lds, const Params& P, int unit, int half) {
;     ...
;             {
;                 const int nt = w & 3, mt0 = 2 * (w >> 2);
;                 f32x4 o[2] = {{0.f, 0.f, 0.f, 0.f}, {0.f, 0.f, 0.f, 0.f}};
;                 {
;                     bf16x8 fq[8], fr0[8], fr1[8];
; #pragma unroll
;                     for (int ks = 0; ks < 8; ++ks) { fq[ks] = rowfrag(TQ, QS, 16 * nt, 32 * ks, lane); fr0[ks] = rowfrag(RT, QS, 16 * mt0, 32 * ks, lane); fr1[ks] = rowfrag(RT, QS, 16 * mt0 + 16, 32 * ks, lane); }
;                     __builtin_amdgcn_sched_barrier(0);
; #pragma unroll
;                     for (int ks = 0; ks < 8; ++ks) { o[0] = mfma16(fr0[ks], fq[ks], o[0]); o[1] = mfma16(fr1[ks], fq[ks], o[1]); }
;                 }
;                 const float qd = exp2f((float)(16 * nt + l15 + 1) * lg2);
;                 o[0] = o[0] * qd; o[1] = o[1] * qd;
;                 {
;                     bf16x8 fat[2], fv0[2], fv1[2];
; #pragma unroll
;                     for (int ks = 0; ks < 2; ++ks) { fat[ks] = rowfrag(AT, VS, 16 * nt, 32 * ks, lane); fv0[ks] = trfrag(TV, VS, 32 * ks, 16 * mt0, lane); fv1[ks] = trfrag(TV, VS, 32 * ks, 16 * mt0 + 16, lane); }
;                     __builtin_amdgcn_sched_barrier(0);
; #pragma unroll
;                     for (int ks = 0; ks < 2; ++ks) { o[0] = mfma16(fv0[ks], fat[ks], o[0]); o[1] = mfma16(fv1[ks], fat[ks], o[1]); }
;                 }
;                 const int tt = r0 + 16 * nt + l15;
;                 float part = 0.f;
; #pragma unroll
;                 for (int i = 0; i < 2; ++i) {
;                     part += (o[i][0] * o[i][0] + o[i][1] * o[i][1]) + (o[i][2] * o[i][2] + o[i][3] * o[i][3]);
;                     *(u32x2*)(OB + (size_t)tt * 4096 + h * 512 + dvs * 64 + 16 * (mt0 + i) + 4 * quad) = pack4(o[i]);
;                 }
;                 part += __shfl_xor(part, 16); part += __shfl_xor(part, 32);
;                 if (quad == 0) unsafeAtomicAdd(rssq + (size_t)tt * 8 + h, part);
;             }
	ds_read_b128 v[134:137], v114
	ds_read_b128 v[138:141], v114 offset:64
	ds_read_b128 v[142:145], v113
	ds_read_b128 v[146:149], v113 offset:64
	ds_read_b128 v[150:153], v113 offset:8704
	ds_read_b128 v[154:157], v113 offset:8768
	ds_read_b128 v[158:161], v114 offset:128
	ds_read_b128 v[162:165], v114 offset:192
	ds_read_b128 v[166:169], v113 offset:128
	ds_read_b128 v[170:173], v113 offset:192
	ds_read_b128 v[174:177], v113 offset:8832
	ds_read_b128 v[182:185], v113 offset:8896
	ds_read_b128 v[186:189], v114 offset:256
	ds_read_b128 v[190:193], v114 offset:320
	ds_read_b128 v[194:197], v113 offset:256
	ds_read_b128 v[198:201], v113 offset:320
	ds_read_b128 v[214:217], v113 offset:8960
	ds_read_b128 v[218:221], v113 offset:9024
	ds_read_b128 v[222:225], v114 offset:384
	ds_read_b128 v[226:229], v114 offset:448
	ds_read_b128 v[230:233], v113 offset:384
	ds_read_b128 v[234:237], v113 offset:448
	ds_read_b128 v[238:241], v113 offset:9088
	ds_read_b128 v[242:245], v113 offset:9152
	s_waitcnt lgkmcnt(14)
	v_mfma_f32_16x16x32_bf16 v[142:145], v[142:145], v[134:137], 0
	v_mfma_f32_16x16x32_bf16 v[142:145], v[146:149], v[138:141], v[142:145]
	v_mfma_f32_16x16x32_bf16 v[142:145], v[166:169], v[158:161], v[142:145]
	v_mfma_f32_16x16x32_bf16 v[134:137], v[150:153], v[134:137], 0
	v_mfma_f32_16x16x32_bf16 v[142:145], v[170:173], v[162:165], v[142:145]
	v_mfma_f32_16x16x32_bf16 v[134:137], v[154:157], v[138:141], v[134:137]
	s_waitcnt lgkmcnt(9)
	v_mfma_f32_16x16x32_bf16 v[142:145], v[194:197], v[186:189], v[142:145]
	v_mfma_f32_16x16x32_bf16 v[134:137], v[174:177], v[158:161], v[134:137]
	s_waitcnt lgkmcnt(8)
	v_mfma_f32_16x16x32_bf16 v[142:145], v[198:201], v[190:193], v[142:145]
	v_mfma_f32_16x16x32_bf16 v[134:137], v[182:185], v[162:165], v[134:137]
	s_waitcnt lgkmcnt(3)
	v_mfma_f32_16x16x32_bf16 v[142:145], v[230:233], v[222:225], v[142:145]
	v_mfma_f32_16x16x32_bf16 v[134:137], v[214:217], v[186:189], v[134:137]
	s_waitcnt lgkmcnt(2)
	v_mfma_f32_16x16x32_bf16 v[142:145], v[234:237], v[226:229], v[142:145]
	v_mfma_f32_16x16x32_bf16 v[134:137], v[218:221], v[190:193], v[134:137]
	s_waitcnt lgkmcnt(1)
	v_mfma_f32_16x16x32_bf16 v[134:137], v[238:241], v[222:225], v[134:137]
	s_nop 4
	v_mul_f32_e64 v140, v70, v144
	v_mul_f32_e64 v141, v71, v145
	v_pk_mul_f32 v[138:139], v[68:69], v[142:143]
	ds_read_b64_tr_b16 v[144:145], v110 offset:640
	ds_read_b64_tr_b16 v[142:143], v110
	ds_read_b64_tr_b16 v[148:149], v110 offset:672
	ds_read_b64_tr_b16 v[146:147], v110 offset:32
	ds_read_b128 v[150:153], v109
	ds_read_b128 v[154:157], v109 offset:64
	ds_read_b64_tr_b16 v[160:161], v92 offset:640
	ds_read_b64_tr_b16 v[158:159], v92
	ds_read_b64_tr_b16 v[164:165], v92 offset:672
	ds_read_b64_tr_b16 v[162:163], v92 offset:32
	s_waitcnt lgkmcnt(10)
	v_mfma_f32_16x16x32_bf16 v[134:137], v[242:245], v[226:229], v[134:137]
	s_nop 7
	v_pk_mul_f32 v[136:137], v[70:71], v[136:137]
	v_pk_mul_f32 v[134:135], v[68:69], v[134:135]
	s_waitcnt lgkmcnt(5)
	v_mfma_f32_16x16x32_bf16 v[138:141], v[142:145], v[150:153], v[138:141]
	s_mov_b32 s0, 0x31c00000
	v_mfma_f32_16x16x32_bf16 v[134:137], v[146:149], v[150:153], v[134:137]
	s_waitcnt lgkmcnt(2)
	v_mfma_f32_16x16x32_bf16 v[138:141], v[158:161], v[154:157], v[138:141]
	s_waitcnt lgkmcnt(0)
	v_mfma_f32_16x16x32_bf16 v[134:137], v[162:165], v[154:157], v[134:137]
	s_nop 5
	v_mul_f32_e32 v73, v139, v139
	v_mul_f32_e32 v133, v141, v141
	v_fmac_f32_e32 v73, v138, v138
	v_fmac_f32_e32 v133, v140, v140
	v_add_f32_e32 v73, v73, v133
	v_mul_f32_e32 v133, v135, v135
	v_mul_f32_e32 v142, v137, v137
	v_fmac_f32_e32 v133, v134, v134
	v_fmac_f32_e32 v142, v136, v136
	v_add_f32_e32 v133, v133, v142
	v_add_f32_e32 v73, v73, v133
	ds_bpermute_b32 v133, v93, v73
	v_cvt_pk_bf16_f32 v138, v138, v139
	v_cvt_pk_bf16_f32 v139, v140, v141
	v_lshl_add_u64 v[140:141], s[92:93], 0, v[90:91]
	v_add_co_u32_e64 v140, s[0:1], s0, v140
	s_waitcnt lgkmcnt(0)
	v_add_f32_e32 v73, v73, v133
	ds_bpermute_b32 v133, v95, v73
	v_addc_co_u32_e64 v141, s[0:1], 0, v141, s[0:1]
	v_cvt_pk_bf16_f32 v134, v134, v135
	v_cvt_pk_bf16_f32 v135, v136, v137
	global_store_dwordx2 v[140:141], v[138:139], off
	global_store_dwordx2 v[140:141], v[134:135], off offset:32
	s_and_saveexec_b64 s[0:1], vcc
	s_cbranch_execz .LBB0_51
	s_waitcnt lgkmcnt(0)
	v_add_f32_e32 v73, v73, v133
	v_lshl_add_u64 v[134:135], s[92:93], 0, v[88:89]
	global_atomic_add_f32 v[134:135], v73, off
	s_branch .LBB0_51
